# attention loop: v_pk_add_f32 beside MFMAs split into scalar v_add_f32 pairs (guide 7.5), on v48
# baseline (speedup 1.0000x reference)
; template <int DQK, bool MLA> ...
;     ...
;     auto substep = [&](f32x16& a, f32x16& b, int knext_ofs, int vofs, int h, int kafter_ofs) __attribute__((always_inline)) {
;         const LAS unsigned char* kb = lds + knext_ofs + r32 * KPITCH + hi * 16;
;         const LAS unsigned char* vb = lds + vofs + r32 * 144 + hi * 16 + h * 64;
;         u32x4 pw0, pw1; bf16x8 vf0[4], vf1[4], kr[3];
;         kr[0] = kp0; kr[1] = kp1;
;         float rs0 = rs_early;
;         __builtin_amdgcn_sched_barrier(0);
; #pragma unroll
;         for (int d0 = 0; d0 < KS; ++d0) {
;             if (d0 + 2 < KS) kr[(d0 + 2) % 3] = *(const LAS bf16x8*)(kb + (d0 + 2) * 32);
;             if (d0 == KS - 3) {
; #pragma unroll
;                 for (int d = 0; d < 4; ++d) vf0[d] = *(const LAS bf16x8*)(vb + d * 4608);
;             }
;             if (d0 == 0) { const f32x16 z16 = {0.f, 0.f, 0.f, 0.f, 0.f, 0.f, 0.f, 0.f, 0.f, 0.f, 0.f, 0.f, 0.f, 0.f, 0.f, 0.f};
;                 b = __builtin_amdgcn_mfma_f32_32x32x16_bf16(kr[0], qf[0], z16, 0, 0, 0); }
;             else b = __builtin_amdgcn_mfma_f32_32x32x16_bf16(kr[d0 % 3], qf[d0], b, 0, 0, 0);
; #pragma unroll
;             for (int e = 6 + (10 * d0) / KS; e < 6 + (10 * (d0 + 1)) / KS; ++e) {
;                 const float x = __builtin_amdgcn_exp2f(a[e]);
;                 a[e] = x;
;                 rs0 += x;
;                 if (e == 7)  { pw0.x = pk(a[0], a[1]); pw0.y = pk(a[2], a[3]);   pw0.z = pk(a[4], a[5]);   pw0.w = pk(a[6], a[7]); }
;                 if (e == 15) { pw1.x = pk(a[8], a[9]); pw1.y = pk(a[10], a[11]); pw1.z = pk(a[12], a[13]); pw1.w = pk(a[14], a[15]); }
;             }
;             __builtin_amdgcn_sched_barrier(0);
;         }
;         l_run += rs0;
;         float rs_n = 0.f;
; #pragma unroll
;         for (int kk = 0; kk < 2; ++kk) {
;             if (kk == 0) {
; #pragma unroll
;                 for (int d = 0; d < 4; ++d) vf1[d] = *(const LAS bf16x8*)(vb + d * 4608 + 32);
;             } else { const LAS unsigned char* ka = lds + kafter_ofs + r32 * KPITCH + hi * 16; kp0 = *(const LAS bf16x8*)(ka); kp1 = *(const LAS bf16x8*)(ka + 32); }
;             const bf16x8 pb = __builtin_bit_cast(bf16x8, kk ? pw1 : pw0);
; #pragma unroll
;             for (int d = 0; d < 4; ++d) {
;                 o[d] = __builtin_amdgcn_mfma_f32_32x32x16_bf16(kk ? vf1[d] : vf0[d], pb, o[d], 0, 0, 0);
.Lattn_ld6_skip:
	s_or_b64 exec, exec, s[34:35]
	ds_read_b128 v[160:163], v193 offset:13024
	v_exp_f32_e32 v195, v74
	s_nop 0
	v_add_f32_e32 v72, v195, v72
	v_lshl_add_u64 v[190:191], v[190:191], 0, s[20:21]
	s_waitcnt lgkmcnt(1)
	v_mfma_f32_32x32x16_bf16 v[80:95], v[210:213], v[124:127], v[80:95]
	ds_read_b128 v[68:71], v193 offset:13056
	s_waitcnt lgkmcnt(1)
	v_mfma_f32_32x32x16_bf16 v[80:95], v[160:163], v[128:131], v[80:95]
	v_exp_f32_e32 v196, v75
	ds_read_b128 v[210:213], v193 offset:13088
	v_add_f32_e32 v160, v196, v72
	s_waitcnt lgkmcnt(1)
	v_mfma_f32_32x32x16_bf16 v[80:95], v[68:71], v[136:139], v[80:95]
	ds_read_b128 v[72:75], v193 offset:13120
	v_exp_f32_e32 v76, v76
	s_nop 0
	v_add_f32_e32 v197, v76, v160
	ds_read_b128 v[68:71], v193 offset:13152
	ds_read_b128 v[160:163], v208
	ds_read_b128 v[214:217], v208 offset:4608
	ds_read_b128 v[218:221], v208 offset:9216
	ds_read_b128 v[222:225], v208 offset:13824
	s_waitcnt lgkmcnt(6)
	v_mfma_f32_32x32x16_bf16 v[80:95], v[210:213], v[144:147], v[80:95]
	v_exp_f32_e32 v77, v77
	s_nop 0
	v_add_f32_e32 v193, v77, v197
	s_waitcnt lgkmcnt(5)
	v_mfma_f32_32x32x16_bf16 v[80:95], v[72:75], v[132:135], v[80:95]
	v_exp_f32_e32 v72, v78
	s_nop 0
	v_add_f32_e32 v73, v72, v193
	s_waitcnt lgkmcnt(4)
	v_mfma_f32_32x32x16_bf16 v[80:95], v[68:71], v[140:143], v[80:95]
	v_exp_f32_e32 v71, v79
	v_cvt_pk_bf16_f32 v68, v194, v186
	v_cvt_pk_bf16_f32 v69, v195, v196
	v_cvt_pk_bf16_f32 v70, v76, v77
	v_add_f32_e32 v73, v71, v73
	v_cvt_pk_bf16_f32 v71, v72, v71
	s_waitcnt lgkmcnt(3)
	v_mfma_f32_32x32x16_bf16 v[48:63], v[160:163], v[64:67], v[48:63]
	v_add_f32_e32 v187, v187, v73
	ds_read_b128 v[72:75], v208 offset:32
	ds_read_b128 v[76:79], v208 offset:4640
	ds_read_b128 v[160:163], v208 offset:9248
	ds_read_b128 v[210:213], v208 offset:13856
	s_nop 1
	v_exp_f32_e32 v186, v80
	v_exp_f32_e32 v193, v81
	s_waitcnt lgkmcnt(6)
	v_mfma_f32_32x32x16_bf16 v[32:47], v[214:217], v[64:67], v[32:47]
	s_waitcnt lgkmcnt(5)
	v_mfma_f32_32x32x16_bf16 v[16:31], v[218:221], v[64:67], v[16:31]
	s_waitcnt lgkmcnt(4)
	v_mfma_f32_32x32x16_bf16 v[0:15], v[222:225], v[64:67], v[0:15]
	s_waitcnt lgkmcnt(3)
	v_mfma_f32_32x32x16_bf16 v[48:63], v[72:75], v[68:71], v[48:63]
	v_exp_f32_e32 v195, v82
	v_add_u32_e32 v194, s72, v183
	v_exp_f32_e32 v196, v83
	ds_read_b128 v[64:67], v194
	ds_read_b128 v[214:217], v194 offset:32
	v_exp_f32_e32 v84, v84
	v_add_f32_e32 v72, 0, v186
	v_exp_f32_e32 v85, v85
	s_waitcnt lgkmcnt(4)
	v_mfma_f32_32x32x16_bf16 v[32:47], v[76:79], v[68:71], v[32:47]
	v_add_f32_e32 v72, v193, v72
	v_add_f32_e32 v72, v195, v72
	v_add_f32_e32 v72, v196, v72
	v_add_f32_e32 v72, v84, v72
	v_add_f32_e32 v197, v85, v72
	s_waitcnt lgkmcnt(3)
	v_mfma_f32_32x32x16_bf16 v[16:31], v[160:163], v[68:71], v[16:31]
	s_waitcnt lgkmcnt(2)
	v_mfma_f32_32x32x16_bf16 v[0:15], v[210:213], v[68:71], v[0:15]
	s_waitcnt lgkmcnt(1)
	v_mfma_f32_32x32x16_bf16 v[64:79], v[64:67], v[100:103], 0
	ds_read_b128 v[80:83], v194 offset:64
	s_waitcnt lgkmcnt(1)
	v_mfma_f32_32x32x16_bf16 v[64:79], v[214:217], v[104:107], v[64:79]
	ds_read_b128 v[160:163], v194 offset:96
	v_exp_f32_e32 v86, v86
	s_nop 0
	v_add_f32_e32 v197, v86, v197
	s_waitcnt lgkmcnt(1)
	v_mfma_f32_32x32x16_bf16 v[64:79], v[80:83], v[108:111], v[64:79]
	ds_read_b128 v[210:213], v194 offset:128
	v_exp_f32_e32 v83, v87
	v_cvt_pk_bf16_f32 v80, v186, v193
	v_cvt_pk_bf16_f32 v81, v195, v196
	v_cvt_pk_bf16_f32 v82, v84, v85
	v_add_f32_e32 v197, v83, v197
	v_cvt_pk_bf16_f32 v83, v86, v83
	s_waitcnt lgkmcnt(1)
	v_mfma_f32_32x32x16_bf16 v[64:79], v[160:163], v[112:115], v[64:79]
	ds_read_b128 v[84:87], v194 offset:160
	v_exp_f32_e32 v186, v88
	s_nop 0
	v_add_f32_e32 v88, v186, v197
	s_waitcnt lgkmcnt(1)
; #define LAS __attribute__((address_space(3)))
; template <int DQK, bool MLA> ...
;     ...
; #pragma unroll
;         for (int kk = 0; kk < 2; ++kk) {
;             if (kk == 0) {
; #pragma unroll
;                 for (int d = 0; d < 4; ++d) vf1[d] = *(const LAS bf16x8*)(vb + d * 4608 + 32);
;             } else { const LAS unsigned char* ka = lds + kafter_ofs + r32 * KPITCH + hi * 16; kp0 = *(const LAS bf16x8*)(ka); kp1 = *(const LAS bf16x8*)(ka + 32); }
;             const bf16x8 pb = __builtin_bit_cast(bf16x8, kk ? pw1 : pw0);
; #pragma unroll
;             for (int d = 0; d < 4; ++d) {
;                 o[d] = __builtin_amdgcn_mfma_f32_32x32x16_bf16(kk ? vf1[d] : vf0[d], pb, o[d], 0, 0, 0);
;                 const int e = 4 * kk + d - 2;
;                 if (e >= 0) { const float x = __builtin_amdgcn_exp2f(b[e]); b[e] = x; rs_n += x; }
;             }
;             __builtin_amdgcn_sched_barrier(0);
;         }
;         rs_early = rs_n;
;     };
;     int kc = 0, kn = KT_BYTES, kn2 = 2 * KT_BYTES;
;     for (int t = 0; t < NT; ++t) {
;         const bool has_k2 = (t + 2 < NT), has_v1 = (t + 1 < NT), active = (t <= tmax_w);
;         const int vofs = 3 * KT_BYTES + (t & 1) * VT_BYTES;
;         if (has_k2) gload_k(t + 2);
;         if (has_v1) gload_v(t + 1);
;         if (active) substep(sX, sY, kc + 32 * KPITCH, vofs, 0, kn);
;         if (active) substep(sY, sX, kn, vofs, 1, kn + 32 * KPITCH);
;         if (has_k2) sts_k(kn2);
;         if (has_v1) sts_v((t + 1) & 1);
;         __syncthreads();
;         const int tmp = kc; kc = kn; kn = kn2; kn2 = tmp;
	v_mfma_f32_32x32x16_bf16 v[64:79], v[210:213], v[116:119], v[64:79]
	ds_read_b128 v[160:163], v194 offset:192
	v_exp_f32_e32 v196, v89
	s_nop 0
	v_add_f32_e32 v88, v196, v88
	s_waitcnt lgkmcnt(1)
	v_mfma_f32_32x32x16_bf16 v[64:79], v[84:87], v[120:123], v[64:79]
	ds_read_b128 v[210:213], v194 offset:224
	v_exp_f32_e32 v226, v90
	s_nop 0
	v_add_f32_e32 v193, v226, v88
	s_waitcnt lgkmcnt(1)
	v_mfma_f32_32x32x16_bf16 v[64:79], v[160:163], v[124:127], v[64:79]
	ds_read_b128 v[84:87], v194 offset:256
	s_waitcnt lgkmcnt(1)
	v_mfma_f32_32x32x16_bf16 v[64:79], v[210:213], v[128:131], v[64:79]
	ds_read_b128 v[160:163], v194 offset:288
	v_exp_f32_e32 v195, v91
	s_waitcnt lgkmcnt(1)
	v_mfma_f32_32x32x16_bf16 v[64:79], v[84:87], v[136:139], v[64:79]
	ds_read_b128 v[88:91], v194 offset:320
	v_exp_f32_e32 v197, v92
	ds_read_b128 v[84:87], v194 offset:352
	ds_read_b128 v[210:213], v208 offset:64
	ds_read_b128 v[214:217], v208 offset:4672
	ds_read_b128 v[218:221], v208 offset:9280
	ds_read_b128 v[222:225], v208 offset:13888
	s_waitcnt lgkmcnt(6)
	v_mfma_f32_32x32x16_bf16 v[64:79], v[160:163], v[144:147], v[64:79]
	v_exp_f32_e32 v209, v93
	s_waitcnt lgkmcnt(5)
	v_mfma_f32_32x32x16_bf16 v[64:79], v[88:91], v[132:135], v[64:79]
	v_exp_f32_e32 v227, v94
	s_waitcnt lgkmcnt(4)
	v_mfma_f32_32x32x16_bf16 v[64:79], v[84:87], v[140:143], v[64:79]
	v_exp_f32_e32 v229, v95
	v_cvt_pk_bf16_f32 v84, v186, v196
	v_cvt_pk_bf16_f32 v85, v226, v195
	v_cvt_pk_bf16_f32 v86, v197, v209
	v_cvt_pk_bf16_f32 v87, v227, v229
	s_waitcnt lgkmcnt(3)
	v_mfma_f32_32x32x16_bf16 v[48:63], v[210:213], v[80:83], v[48:63]
	s_add_i32 s98, s68, 1
	s_bitcmp1_b32 s98, 0
	s_cselect_b32 s98, 0x4800, 0
	v_add_u32_e32 v230, s71, v172
	v_add_u32_e32 v231, s71, v174
	v_add_u32_e32 v232, s71, v184
	v_add_u32_e32 v233, s98, v173
	s_waitcnt vmcnt(4)
	ds_write_b128 v230, v[148:151]
	v_exp_f32_e32 v64, v64
	v_exp_f32_e32 v65, v65
	s_waitcnt lgkmcnt(3)
	v_mfma_f32_32x32x16_bf16 v[32:47], v[214:217], v[80:83], v[32:47]
	ds_read_b128 v[88:91], v208 offset:96
	ds_read_b128 v[92:95], v208 offset:4704
	ds_read_b128 v[210:213], v208 offset:9312
	ds_read_b128 v[214:217], v208 offset:13920
	s_waitcnt lgkmcnt(6)
	v_mfma_f32_32x32x16_bf16 v[16:31], v[218:221], v[80:83], v[16:31]
	s_waitcnt vmcnt(3)
	ds_write_b128 v231, v[152:155]
	s_waitcnt lgkmcnt(6)
	v_mfma_f32_32x32x16_bf16 v[0:15], v[222:225], v[80:83], v[0:15]
	v_exp_f32_e32 v66, v66
	s_waitcnt vmcnt(2)
	ds_write_b128 v232, v[156:159] offset:256
	s_waitcnt lgkmcnt(5)
	v_mfma_f32_32x32x16_bf16 v[48:63], v[88:91], v[84:87], v[48:63]
	v_exp_f32_e32 v67, v67
	ds_read_b128 v[80:83], v194 offset:12800
	ds_read_b128 v[160:163], v194 offset:12832
	v_exp_f32_e32 v68, v68
	v_mov_b32_e32 v194, v64
	v_exp_f32_e32 v69, v69
	v_add_f32_e32 v88, v194, v192
	v_add_f32_e32 v89, v195, v193
	v_mov_b32_e32 v196, v65
	s_waitcnt lgkmcnt(6)
	v_mfma_f32_32x32x16_bf16 v[32:47], v[92:95], v[84:87], v[32:47]
	v_add_f32_e64 v88, v196, v88
	v_add_f32_e64 v89, v197, v89
	v_mov_b32_e32 v208, v66
	v_add_f32_e64 v88, v208, v88
	v_add_f32_e64 v89, v209, v89
	v_mov_b32_e32 v226, v67
	v_add_f32_e32 v88, v226, v88
	v_add_f32_e32 v89, v227, v89
	v_mov_b32_e32 v228, v68
	v_add_f32_e32 v88, v228, v88
	v_add_f32_e32 v89, v229, v89
	s_waitcnt vmcnt(1)
	ds_write_b128 v233, v[164:167]
	s_waitcnt lgkmcnt(6)
	v_mfma_f32_32x32x16_bf16 v[16:31], v[210:213], v[84:87], v[16:31]
	s_waitcnt vmcnt(0)
	s_add_i32 s68, s68, 1
	s_add_i32 s73, s71, 0
	s_bitcmp1_b32 s68, 0
	s_cselect_b64 s[34:35], -1, 0
	s_and_b64 s[66:67], s[34:35], exec
	s_cselect_b32 s66, 0x4800, 0
	s_and_saveexec_b64 s[66:67], s[4:5]
	ds_write_b128 v233, v[96:99] offset:16384
	s_or_b64 exec, exec, s[66:67]
	ds_write_b128 v233, v[168:171] offset:8192
	v_mov_b32_e32 v186, v69
	v_add_f32_e64 v186, v186, v88
	v_add_f32_e64 v187, v187, v89
	s_waitcnt lgkmcnt(7)
	v_mfma_f32_32x32x16_bf16 v[0:15], v[214:217], v[84:87], v[0:15]
	s_branch .Lattn_wtail
